# P4 epilogue: x prefetch loads global instead of flat (no lgkmcnt coupling), per-group wait leaves the row-sum atomic in flight
# baseline (speedup 1.0000x reference)
.LBB0_675:
	s_lshl_b32 s38, s4, 8
	v_add_u32_e32 v128, s38, v157
	v_ashrrev_i32_e32 v129, 31, v128
	s_lshl_b32 s6, s55, 8
	v_lshlrev_b64 v[128:129], 11, v[128:129]
	s_ashr_i32 s7, s6, 31
	v_lshl_add_u64 v[178:179], v[128:129], 0, s[6:7]
	v_or_b32_e32 v178, v178, v156
	v_lshl_add_u64 v[128:129], v[178:179], 2, s[8:9]
	global_load_dwordx4 v[162:165], v[128:129], off
	global_load_dwordx4 v[170:173], v[128:129], off offset:16
	global_load_dwordx4 v[192:195], v[128:129], off offset:512
	global_load_dwordx4 v[196:199], v[128:129], off offset:528
	v_lshl_add_u64 v[182:183], v[128:129], 0, s[16:17]
	global_load_dwordx4 v[140:143], v[182:183], off
	global_load_dwordx4 v[136:139], v[182:183], off offset:16
	global_load_dwordx4 v[132:135], v[182:183], off offset:512
	global_load_dwordx4 v[128:131], v[182:183], off offset:528
	v_and_b32_e32 v167, 64, v187
	v_xor_b32_e32 v166, 16, v187
	v_add_u32_e32 v180, 64, v167
	v_cmp_lt_i32_e32 vcc, v166, v180
	s_ashr_i32 s39, s38, 31
	s_waitcnt vmcnt(0)
	v_pk_add_f32 v[168:169], v[126:127], v[164:165]
	v_cndmask_b32_e32 v166, v187, v166, vcc
	v_lshlrev_b32_e32 v191, 2, v166
	v_pk_add_f32 v[176:177], v[124:125], v[162:163]
	v_pk_add_f32 v[166:167], v[122:123], v[172:173]
	v_pk_add_f32 v[174:175], v[120:121], v[170:171]
	v_pk_add_f32 v[164:165], v[118:119], v[194:195]
	v_pk_add_f32 v[172:173], v[116:117], v[192:193]
	v_pk_add_f32 v[162:163], v[114:115], v[198:199]
	v_pk_add_f32 v[170:171], v[112:113], v[196:197]
	v_mul_f32_e32 v112, v177, v177
	v_mul_f32_e32 v113, v169, v169
	v_mul_f32_e32 v114, v175, v175
	v_mul_f32_e32 v115, v167, v167
	v_mul_f32_e32 v116, v173, v173
	v_mul_f32_e32 v117, v165, v165
	v_fmac_f32_e32 v112, v176, v176
	v_fmac_f32_e32 v113, v168, v168
	v_fmac_f32_e32 v114, v174, v174
	v_fmac_f32_e32 v115, v166, v166
	v_mul_f32_e32 v118, v171, v171
	v_mul_f32_e32 v119, v163, v163
	v_fmac_f32_e32 v116, v172, v172
	v_fmac_f32_e32 v117, v164, v164
	v_add_f32_e32 v112, v112, v113
	v_add_f32_e32 v113, v114, v115
	v_fmac_f32_e32 v118, v170, v170
	v_fmac_f32_e32 v119, v162, v162
	v_add_f32_e32 v114, v116, v117
	v_add_f32_e32 v112, v112, v113
	v_add_f32_e32 v115, v118, v119
	v_add_f32_e32 v112, v112, v114
	v_add_f32_e32 v112, v112, v115
	ds_bpermute_b32 v113, v191, v112
	v_xor_b32_e32 v114, 32, v187
	v_cmp_lt_i32_e32 vcc, v114, v180
	v_lshl_add_u64 v[180:181], s[38:39], 2, v[152:153]
	s_waitcnt lgkmcnt(0)
	v_add_f32_e32 v112, v112, v113
	v_cndmask_b32_e32 v114, v187, v114, vcc
	v_lshlrev_b32_e32 v192, 2, v114
	ds_bpermute_b32 v113, v192, v112
	s_and_saveexec_b64 s[38:39], s[0:1]
	s_cbranch_execz .LBB0_677
	s_waitcnt lgkmcnt(0)
	v_add_f32_e32 v112, v112, v113
	global_atomic_add_f32 v[180:181], v112, off
.LBB0_677:
	s_or_b64 exec, exec, s[38:39]
	v_lshl_add_u64 v[182:183], v[182:183], 0, s[16:17]
	v_pk_add_f32 v[142:143], v[110:111], v[142:143]
	v_pk_add_f32 v[140:141], v[108:109], v[140:141]
	v_pk_add_f32 v[138:139], v[106:107], v[138:139]
	global_load_dwordx4 v[124:127], v[182:183], off
	global_load_dwordx4 v[120:123], v[182:183], off offset:16
	global_load_dwordx4 v[116:119], v[182:183], off offset:512
	s_waitcnt lgkmcnt(0)
	global_load_dwordx4 v[112:115], v[182:183], off offset:528
	v_pk_add_f32 v[136:137], v[104:105], v[136:137]
	v_mul_f32_e32 v108, v141, v141
	v_mul_f32_e32 v109, v143, v143
	v_mul_f32_e32 v104, v137, v137
	v_mul_f32_e32 v105, v139, v139
	v_pk_add_f32 v[134:135], v[102:103], v[134:135]
	v_pk_add_f32 v[132:133], v[100:101], v[132:133]
	v_fmac_f32_e32 v108, v140, v140
	v_fmac_f32_e32 v109, v142, v142
	v_fmac_f32_e32 v104, v136, v136
	v_fmac_f32_e32 v105, v138, v138
	v_mul_f32_e32 v100, v133, v133
	v_mul_f32_e32 v101, v135, v135
	v_pk_add_f32 v[130:131], v[98:99], v[130:131]
	v_pk_add_f32 v[128:129], v[96:97], v[128:129]
	v_add_f32_e32 v108, v108, v109
	v_add_f32_e32 v104, v104, v105
	v_fmac_f32_e32 v100, v132, v132
	v_fmac_f32_e32 v101, v134, v134
	v_mul_f32_e32 v96, v129, v129
	v_mul_f32_e32 v97, v131, v131
	v_add_f32_e32 v104, v108, v104
	v_add_f32_e32 v100, v100, v101
	v_fmac_f32_e32 v96, v128, v128
	v_fmac_f32_e32 v97, v130, v130
	v_add_f32_e32 v100, v104, v100
	v_add_f32_e32 v96, v96, v97
	v_add_f32_e32 v96, v100, v96
	ds_bpermute_b32 v97, v191, v96
	s_waitcnt lgkmcnt(0)
	v_add_f32_e32 v96, v96, v97
	ds_bpermute_b32 v97, v192, v96
	s_and_saveexec_b64 s[38:39], s[0:1]
	s_cbranch_execz .LBB0_679
	s_waitcnt lgkmcnt(0)
	v_add_f32_e32 v96, v96, v97
	global_atomic_add_f32 v[180:181], v96, off offset:64
.LBB0_679:
	s_or_b64 exec, exec, s[38:39]
	v_lshl_add_u64 v[182:183], v[182:183], 0, s[16:17]
	s_waitcnt vmcnt(1)
	v_pk_add_f32 v[126:127], v[94:95], v[126:127]
	v_pk_add_f32 v[124:125], v[92:93], v[124:125]
	v_pk_add_f32 v[122:123], v[90:91], v[122:123]
	global_load_dwordx4 v[108:111], v[182:183], off
	global_load_dwordx4 v[104:107], v[182:183], off offset:16
	global_load_dwordx4 v[100:103], v[182:183], off offset:512
	s_waitcnt lgkmcnt(0)
	global_load_dwordx4 v[96:99], v[182:183], off offset:528
	v_pk_add_f32 v[120:121], v[88:89], v[120:121]
	v_mul_f32_e32 v92, v125, v125
	v_mul_f32_e32 v93, v127, v127
	v_mul_f32_e32 v88, v121, v121
	v_mul_f32_e32 v89, v123, v123
	v_pk_add_f32 v[118:119], v[86:87], v[118:119]
	v_pk_add_f32 v[116:117], v[84:85], v[116:117]
	v_fmac_f32_e32 v92, v124, v124
	v_fmac_f32_e32 v93, v126, v126
	v_fmac_f32_e32 v88, v120, v120
	v_fmac_f32_e32 v89, v122, v122
	v_mul_f32_e32 v84, v117, v117
	v_mul_f32_e32 v85, v119, v119
	v_pk_add_f32 v[114:115], v[82:83], v[114:115]
	v_pk_add_f32 v[112:113], v[80:81], v[112:113]
	v_add_f32_e32 v92, v92, v93
	v_add_f32_e32 v88, v88, v89
	v_fmac_f32_e32 v84, v116, v116
	v_fmac_f32_e32 v85, v118, v118
	v_mul_f32_e32 v80, v113, v113
	v_mul_f32_e32 v81, v115, v115
	v_add_f32_e32 v88, v92, v88
	v_add_f32_e32 v84, v84, v85
	v_fmac_f32_e32 v80, v112, v112
	v_fmac_f32_e32 v81, v114, v114
	v_add_f32_e32 v84, v88, v84
	v_add_f32_e32 v80, v80, v81
	v_add_f32_e32 v80, v84, v80
	ds_bpermute_b32 v81, v191, v80
	s_waitcnt lgkmcnt(0)
	v_add_f32_e32 v80, v80, v81
	ds_bpermute_b32 v81, v192, v80
	s_and_saveexec_b64 s[38:39], s[0:1]
	s_cbranch_execz .LBB0_681
	s_waitcnt lgkmcnt(0)
	v_add_f32_e32 v80, v80, v81
	global_atomic_add_f32 v[180:181], v80, off offset:128
.LBB0_681:
	s_or_b64 exec, exec, s[38:39]
	v_lshl_add_u64 v[182:183], v[182:183], 0, s[20:21]
	s_waitcnt vmcnt(1)
	v_pk_add_f32 v[110:111], v[78:79], v[110:111]
	v_pk_add_f32 v[108:109], v[76:77], v[108:109]
	v_pk_add_f32 v[106:107], v[74:75], v[106:107]
	global_load_dwordx4 v[92:95], v[182:183], off
	global_load_dwordx4 v[88:91], v[182:183], off offset:16
	global_load_dwordx4 v[84:87], v[182:183], off offset:512
	s_waitcnt lgkmcnt(0)
	global_load_dwordx4 v[80:83], v[182:183], off offset:528
	v_pk_add_f32 v[104:105], v[72:73], v[104:105]
	v_mul_f32_e32 v76, v109, v109
	v_mul_f32_e32 v77, v111, v111
	v_mul_f32_e32 v72, v105, v105
	v_mul_f32_e32 v73, v107, v107
	v_pk_add_f32 v[102:103], v[70:71], v[102:103]
	v_pk_add_f32 v[100:101], v[68:69], v[100:101]
	v_fmac_f32_e32 v76, v108, v108
	v_fmac_f32_e32 v77, v110, v110
	v_fmac_f32_e32 v72, v104, v104
	v_fmac_f32_e32 v73, v106, v106
	v_mul_f32_e32 v68, v101, v101
	v_mul_f32_e32 v69, v103, v103
	v_pk_add_f32 v[98:99], v[66:67], v[98:99]
	v_pk_add_f32 v[96:97], v[64:65], v[96:97]
	v_add_f32_e32 v76, v76, v77
	v_add_f32_e32 v72, v72, v73
	v_fmac_f32_e32 v68, v100, v100
	v_fmac_f32_e32 v69, v102, v102
	v_mul_f32_e32 v64, v97, v97
	v_mul_f32_e32 v65, v99, v99
	v_add_f32_e32 v72, v76, v72
	v_add_f32_e32 v68, v68, v69
	v_fmac_f32_e32 v64, v96, v96
	v_fmac_f32_e32 v65, v98, v98
	v_add_f32_e32 v68, v72, v68
	v_add_f32_e32 v64, v64, v65
	v_add_f32_e32 v64, v68, v64
	ds_bpermute_b32 v65, v191, v64
	s_waitcnt lgkmcnt(0)
	v_add_f32_e32 v64, v64, v65
	ds_bpermute_b32 v65, v192, v64
	s_and_saveexec_b64 s[38:39], s[0:1]
	s_cbranch_execz .LBB0_683
	s_waitcnt lgkmcnt(0)
	v_add_f32_e32 v64, v64, v65
	global_atomic_add_f32 v[180:181], v64, off offset:192
.LBB0_683:
	s_or_b64 exec, exec, s[38:39]
	v_lshl_add_u64 v[182:183], v[182:183], 0, s[16:17]
	s_waitcnt vmcnt(1)
	v_pk_add_f32 v[94:95], v[62:63], v[94:95]
	v_pk_add_f32 v[92:93], v[60:61], v[92:93]
	v_pk_add_f32 v[90:91], v[58:59], v[90:91]
	global_load_dwordx4 v[76:79], v[182:183], off
	global_load_dwordx4 v[72:75], v[182:183], off offset:16
	global_load_dwordx4 v[68:71], v[182:183], off offset:512
	s_waitcnt lgkmcnt(0)
	global_load_dwordx4 v[64:67], v[182:183], off offset:528
	v_pk_add_f32 v[88:89], v[56:57], v[88:89]
	v_mul_f32_e32 v60, v93, v93
	v_mul_f32_e32 v61, v95, v95
	v_mul_f32_e32 v56, v89, v89
	v_mul_f32_e32 v57, v91, v91
	v_pk_add_f32 v[86:87], v[54:55], v[86:87]
	v_pk_add_f32 v[84:85], v[52:53], v[84:85]
	v_fmac_f32_e32 v60, v92, v92
	v_fmac_f32_e32 v61, v94, v94
	v_fmac_f32_e32 v56, v88, v88
	v_fmac_f32_e32 v57, v90, v90
	v_mul_f32_e32 v52, v85, v85
	v_mul_f32_e32 v53, v87, v87
	v_pk_add_f32 v[82:83], v[50:51], v[82:83]
	v_pk_add_f32 v[80:81], v[48:49], v[80:81]
	v_add_f32_e32 v60, v60, v61
	v_add_f32_e32 v56, v56, v57
	v_fmac_f32_e32 v52, v84, v84
	v_fmac_f32_e32 v53, v86, v86
	v_mul_f32_e32 v48, v81, v81
	v_mul_f32_e32 v49, v83, v83
	v_add_f32_e32 v56, v60, v56
	v_add_f32_e32 v52, v52, v53
	v_fmac_f32_e32 v48, v80, v80
	v_fmac_f32_e32 v49, v82, v82
	v_add_f32_e32 v52, v56, v52
	v_add_f32_e32 v48, v48, v49
	v_add_f32_e32 v48, v52, v48
	ds_bpermute_b32 v49, v191, v48
	s_waitcnt lgkmcnt(0)
	v_add_f32_e32 v48, v48, v49
	ds_bpermute_b32 v49, v192, v48
	s_and_saveexec_b64 s[38:39], s[0:1]
	s_cbranch_execz .LBB0_685
	s_waitcnt lgkmcnt(0)
	v_add_f32_e32 v48, v48, v49
	global_atomic_add_f32 v[180:181], v48, off offset:512
.LBB0_685:
	s_or_b64 exec, exec, s[38:39]
	v_lshl_add_u64 v[182:183], v[182:183], 0, s[16:17]
	s_waitcnt vmcnt(1)
	v_pk_add_f32 v[78:79], v[46:47], v[78:79]
	v_pk_add_f32 v[76:77], v[44:45], v[76:77]
	v_pk_add_f32 v[74:75], v[42:43], v[74:75]
	global_load_dwordx4 v[60:63], v[182:183], off
	global_load_dwordx4 v[56:59], v[182:183], off offset:16
	global_load_dwordx4 v[52:55], v[182:183], off offset:512
	s_waitcnt lgkmcnt(0)
	global_load_dwordx4 v[48:51], v[182:183], off offset:528
	v_pk_add_f32 v[72:73], v[40:41], v[72:73]
	v_mul_f32_e32 v44, v77, v77
	v_mul_f32_e32 v45, v79, v79
	v_mul_f32_e32 v40, v73, v73
	v_mul_f32_e32 v41, v75, v75
	v_pk_add_f32 v[70:71], v[38:39], v[70:71]
	v_pk_add_f32 v[68:69], v[36:37], v[68:69]
	v_fmac_f32_e32 v44, v76, v76
	v_fmac_f32_e32 v45, v78, v78
	v_fmac_f32_e32 v40, v72, v72
	v_fmac_f32_e32 v41, v74, v74
	v_mul_f32_e32 v36, v69, v69
	v_mul_f32_e32 v37, v71, v71
	v_pk_add_f32 v[66:67], v[34:35], v[66:67]
	v_pk_add_f32 v[64:65], v[32:33], v[64:65]
	v_add_f32_e32 v44, v44, v45
	v_add_f32_e32 v40, v40, v41
	v_fmac_f32_e32 v36, v68, v68
	v_fmac_f32_e32 v37, v70, v70
	v_mul_f32_e32 v32, v65, v65
	v_mul_f32_e32 v33, v67, v67
	v_add_f32_e32 v40, v44, v40
	v_add_f32_e32 v36, v36, v37
	v_fmac_f32_e32 v32, v64, v64
	v_fmac_f32_e32 v33, v66, v66
	v_add_f32_e32 v36, v40, v36
	v_add_f32_e32 v32, v32, v33
	v_add_f32_e32 v32, v36, v32
	ds_bpermute_b32 v33, v191, v32
	s_waitcnt lgkmcnt(0)
	v_add_f32_e32 v32, v32, v33
	ds_bpermute_b32 v33, v192, v32
	s_and_saveexec_b64 s[38:39], s[0:1]
	s_cbranch_execz .LBB0_687
	s_waitcnt lgkmcnt(0)
	v_add_f32_e32 v32, v32, v33
	global_atomic_add_f32 v[180:181], v32, off offset:576
.LBB0_687:
	s_or_b64 exec, exec, s[38:39]
	v_lshl_add_u64 v[182:183], v[182:183], 0, s[16:17]
	s_waitcnt vmcnt(1)
	v_pk_add_f32 v[62:63], v[30:31], v[62:63]
	v_pk_add_f32 v[60:61], v[28:29], v[60:61]
	v_pk_add_f32 v[58:59], v[26:27], v[58:59]
	global_load_dwordx4 v[44:47], v[182:183], off
	global_load_dwordx4 v[40:43], v[182:183], off offset:16
	global_load_dwordx4 v[36:39], v[182:183], off offset:512
	s_waitcnt lgkmcnt(0)
	global_load_dwordx4 v[32:35], v[182:183], off offset:528
	v_pk_add_f32 v[56:57], v[24:25], v[56:57]
	v_mul_f32_e32 v28, v61, v61
	v_mul_f32_e32 v29, v63, v63
	v_mul_f32_e32 v24, v57, v57
	v_mul_f32_e32 v25, v59, v59
	v_pk_add_f32 v[54:55], v[22:23], v[54:55]
	v_pk_add_f32 v[52:53], v[20:21], v[52:53]
	v_fmac_f32_e32 v28, v60, v60
	v_fmac_f32_e32 v29, v62, v62
	v_fmac_f32_e32 v24, v56, v56
	v_fmac_f32_e32 v25, v58, v58
	v_mul_f32_e32 v20, v53, v53
	v_mul_f32_e32 v21, v55, v55
	v_add_f32_e32 v28, v28, v29
	v_add_f32_e32 v24, v24, v25
	v_fmac_f32_e32 v20, v52, v52
	v_fmac_f32_e32 v21, v54, v54
	v_add_f32_e32 v24, v28, v24
	v_add_f32_e32 v20, v20, v21
	v_add_f32_e32 v20, v24, v20
	v_pk_add_f32 v[24:25], v[18:19], v[50:51]
	v_pk_add_f32 v[48:49], v[16:17], v[48:49]
	v_mul_f32_e32 v17, v25, v25
	v_mul_f32_e32 v16, v49, v49
	v_fmac_f32_e32 v16, v48, v48
	v_fmac_f32_e32 v17, v24, v24
	v_add_f32_e32 v16, v16, v17
	v_add_f32_e32 v16, v20, v16
	ds_bpermute_b32 v17, v191, v16
	s_waitcnt lgkmcnt(0)
	v_add_f32_e32 v16, v16, v17
	ds_bpermute_b32 v17, v192, v16
	s_and_saveexec_b64 s[38:39], s[0:1]
	s_cbranch_execz .LBB0_689
	s_waitcnt lgkmcnt(0)
	v_add_f32_e32 v16, v16, v17
	global_atomic_add_f32 v[180:181], v16, off offset:640
.LBB0_689:
	s_or_b64 exec, exec, s[38:39]
	s_waitcnt vmcnt(1) lgkmcnt(0)
	v_pk_add_f32 v[16:17], v[14:15], v[46:47]
	v_pk_add_f32 v[20:21], v[12:13], v[44:45]
	v_pk_add_f32 v[18:19], v[10:11], v[42:43]
	v_pk_add_f32 v[26:27], v[8:9], v[40:41]
	v_mul_f32_e32 v12, v21, v21
	v_mul_f32_e32 v13, v17, v17
	v_mul_f32_e32 v8, v27, v27
	v_mul_f32_e32 v9, v19, v19
	v_pk_add_f32 v[22:23], v[6:7], v[38:39]
	v_pk_add_f32 v[30:31], v[4:5], v[36:37]
	v_fmac_f32_e32 v12, v20, v20
	v_fmac_f32_e32 v13, v16, v16
	v_fmac_f32_e32 v8, v26, v26
	v_fmac_f32_e32 v9, v18, v18
	v_mul_f32_e32 v4, v31, v31
	v_mul_f32_e32 v5, v23, v23
	v_pk_add_f32 v[28:29], v[2:3], v[34:35]
	v_pk_add_f32 v[32:33], v[0:1], v[32:33]
	v_add_f32_e32 v12, v12, v13
	v_add_f32_e32 v8, v8, v9
	v_fmac_f32_e32 v4, v30, v30
	v_fmac_f32_e32 v5, v22, v22
	v_mul_f32_e32 v0, v33, v33
	v_mul_f32_e32 v1, v29, v29
	v_add_f32_e32 v8, v12, v8
	v_add_f32_e32 v4, v4, v5
	v_fmac_f32_e32 v0, v32, v32
	v_fmac_f32_e32 v1, v28, v28
	v_add_f32_e32 v4, v8, v4
	v_add_f32_e32 v0, v0, v1
	v_add_f32_e32 v0, v4, v0
	ds_bpermute_b32 v1, v191, v0
	v_lshl_add_u64 v[2:3], v[182:183], 0, s[20:21]
	s_waitcnt lgkmcnt(0)
	v_add_f32_e32 v0, v0, v1
	ds_bpermute_b32 v1, v192, v0
	s_and_saveexec_b64 s[38:39], s[0:1]
	s_cbranch_execz .LBB0_691
	s_waitcnt lgkmcnt(0)
	v_add_f32_e32 v0, v0, v1
	global_atomic_add_f32 v[180:181], v0, off offset:704
